# mod_job weight loads software-prefetched 8 iterations deep
# speedup vs baseline: 1.0157x; 1.0017x over previous
.LBB0_942:
	s_mov_b64 s[14:15], 0x12000
	v_add_co_u32_e32 v204, vcc, s71, v40
	global_load_dwordx4 v[140:143], v[40:41], off
	v_addc_co_u32_e32 v205, vcc, 0, v41, vcc
	global_load_dwordx4 v[144:147], v[204:205], off
	v_lshl_add_u64 v[40:41], v[40:41], 0, s[14:15]
	v_add_co_u32_e32 v204, vcc, s71, v40
	global_load_dwordx4 v[148:151], v[40:41], off
	v_addc_co_u32_e32 v205, vcc, 0, v41, vcc
	global_load_dwordx4 v[152:155], v[204:205], off
	v_lshl_add_u64 v[40:41], v[40:41], 0, s[14:15]
	v_add_co_u32_e32 v204, vcc, s71, v40
	global_load_dwordx4 v[156:159], v[40:41], off
	v_addc_co_u32_e32 v205, vcc, 0, v41, vcc
	global_load_dwordx4 v[160:163], v[204:205], off
	v_lshl_add_u64 v[40:41], v[40:41], 0, s[14:15]
	v_add_co_u32_e32 v204, vcc, s71, v40
	global_load_dwordx4 v[164:167], v[40:41], off
	v_addc_co_u32_e32 v205, vcc, 0, v41, vcc
	global_load_dwordx4 v[168:171], v[204:205], off
	v_lshl_add_u64 v[40:41], v[40:41], 0, s[14:15]
	v_add_co_u32_e32 v204, vcc, s71, v40
	global_load_dwordx4 v[172:175], v[40:41], off
	v_addc_co_u32_e32 v205, vcc, 0, v41, vcc
	global_load_dwordx4 v[176:179], v[204:205], off
	v_lshl_add_u64 v[40:41], v[40:41], 0, s[14:15]
	v_add_co_u32_e32 v204, vcc, s71, v40
	global_load_dwordx4 v[180:183], v[40:41], off
	v_addc_co_u32_e32 v205, vcc, 0, v41, vcc
	global_load_dwordx4 v[184:187], v[204:205], off
	v_lshl_add_u64 v[40:41], v[40:41], 0, s[14:15]
	v_add_co_u32_e32 v204, vcc, s71, v40
	global_load_dwordx4 v[188:191], v[40:41], off
	v_addc_co_u32_e32 v205, vcc, 0, v41, vcc
	global_load_dwordx4 v[192:195], v[204:205], off
	v_lshl_add_u64 v[40:41], v[40:41], 0, s[14:15]
	v_add_co_u32_e32 v204, vcc, s71, v40
	global_load_dwordx4 v[196:199], v[40:41], off
	v_addc_co_u32_e32 v205, vcc, 0, v41, vcc
	global_load_dwordx4 v[200:203], v[204:205], off
	v_lshl_add_u64 v[40:41], v[40:41], 0, s[14:15]
	s_movk_i32 s100, 3
.Lmod_trip:
	v_add_u32_e32 v66, s9, v39
	ds_read2st64_b64 v[50:53], v66 offset1:8
	ds_read2st64_b64 v[54:57], v66 offset0:16 offset1:24
	ds_read2st64_b64 v[58:61], v66 offset0:32 offset1:40
	ds_read2st64_b64 v[62:65], v66 offset0:48 offset1:56
	ds_read_b64 v[66:67], v66 offset:32768
	s_add_i32 s9, s9, 8
	s_waitcnt vmcnt(14) lgkmcnt(0)
	v_pk_fma_f32 v[36:37], v[142:143], v[50:51], v[36:37] op_sel_hi:[1,0,1]
	v_pk_fma_f32 v[34:35], v[140:141], v[50:51], v[34:35] op_sel_hi:[1,0,1]
	v_pk_fma_f32 v[32:33], v[142:143], v[52:53], v[32:33] op_sel_hi:[1,0,1]
	v_pk_fma_f32 v[30:31], v[140:141], v[52:53], v[30:31] op_sel_hi:[1,0,1]
	v_pk_fma_f32 v[28:29], v[142:143], v[54:55], v[28:29] op_sel_hi:[1,0,1]
	v_pk_fma_f32 v[26:27], v[140:141], v[54:55], v[26:27] op_sel_hi:[1,0,1]
	v_pk_fma_f32 v[24:25], v[142:143], v[56:57], v[24:25] op_sel_hi:[1,0,1]
	v_pk_fma_f32 v[22:23], v[140:141], v[56:57], v[22:23] op_sel_hi:[1,0,1]
	v_pk_fma_f32 v[20:21], v[142:143], v[58:59], v[20:21] op_sel_hi:[1,0,1]
	v_pk_fma_f32 v[18:19], v[140:141], v[58:59], v[18:19] op_sel_hi:[1,0,1]
	v_pk_fma_f32 v[16:17], v[142:143], v[60:61], v[16:17] op_sel_hi:[1,0,1]
	v_pk_fma_f32 v[14:15], v[140:141], v[60:61], v[14:15] op_sel_hi:[1,0,1]
	v_pk_fma_f32 v[12:13], v[142:143], v[62:63], v[12:13] op_sel_hi:[1,0,1]
	v_pk_fma_f32 v[10:11], v[140:141], v[62:63], v[10:11] op_sel_hi:[1,0,1]
	v_pk_fma_f32 v[8:9], v[142:143], v[64:65], v[8:9] op_sel_hi:[1,0,1]
	v_pk_fma_f32 v[6:7], v[140:141], v[64:65], v[6:7] op_sel_hi:[1,0,1]
	v_pk_fma_f32 v[4:5], v[142:143], v[66:67], v[4:5] op_sel_hi:[1,0,1]
	v_pk_fma_f32 v[2:3], v[140:141], v[66:67], v[2:3] op_sel_hi:[1,0,1]
	v_pk_fma_f32 v[36:37], v[146:147], v[50:51], v[36:37] op_sel:[0,1,0]
	v_pk_fma_f32 v[34:35], v[144:145], v[50:51], v[34:35] op_sel:[0,1,0]
	v_pk_fma_f32 v[32:33], v[146:147], v[52:53], v[32:33] op_sel:[0,1,0]
	v_pk_fma_f32 v[30:31], v[144:145], v[52:53], v[30:31] op_sel:[0,1,0]
	v_pk_fma_f32 v[28:29], v[146:147], v[54:55], v[28:29] op_sel:[0,1,0]
	v_pk_fma_f32 v[26:27], v[144:145], v[54:55], v[26:27] op_sel:[0,1,0]
	v_pk_fma_f32 v[24:25], v[146:147], v[56:57], v[24:25] op_sel:[0,1,0]
	v_pk_fma_f32 v[22:23], v[144:145], v[56:57], v[22:23] op_sel:[0,1,0]
	v_pk_fma_f32 v[20:21], v[146:147], v[58:59], v[20:21] op_sel:[0,1,0]
	v_pk_fma_f32 v[18:19], v[144:145], v[58:59], v[18:19] op_sel:[0,1,0]
	v_pk_fma_f32 v[16:17], v[146:147], v[60:61], v[16:17] op_sel:[0,1,0]
	v_pk_fma_f32 v[14:15], v[144:145], v[60:61], v[14:15] op_sel:[0,1,0]
	v_pk_fma_f32 v[12:13], v[146:147], v[62:63], v[12:13] op_sel:[0,1,0]
	v_pk_fma_f32 v[10:11], v[144:145], v[62:63], v[10:11] op_sel:[0,1,0]
	v_pk_fma_f32 v[8:9], v[146:147], v[64:65], v[8:9] op_sel:[0,1,0]
	v_pk_fma_f32 v[6:7], v[144:145], v[64:65], v[6:7] op_sel:[0,1,0]
	v_pk_fma_f32 v[4:5], v[146:147], v[66:67], v[4:5] op_sel:[0,1,0]
	v_pk_fma_f32 v[2:3], v[144:145], v[66:67], v[2:3] op_sel:[0,1,0]
	v_add_co_u32_e32 v204, vcc, s71, v40
	global_load_dwordx4 v[140:143], v[40:41], off
	v_addc_co_u32_e32 v205, vcc, 0, v41, vcc
	global_load_dwordx4 v[144:147], v[204:205], off
	v_lshl_add_u64 v[40:41], v[40:41], 0, s[14:15]
	v_add_u32_e32 v66, s9, v39
	ds_read2st64_b64 v[50:53], v66 offset1:8
	ds_read2st64_b64 v[54:57], v66 offset0:16 offset1:24
	ds_read2st64_b64 v[58:61], v66 offset0:32 offset1:40
	ds_read2st64_b64 v[62:65], v66 offset0:48 offset1:56
	ds_read_b64 v[66:67], v66 offset:32768
	s_add_i32 s9, s9, 8
	s_waitcnt vmcnt(14) lgkmcnt(0)
	v_pk_fma_f32 v[36:37], v[150:151], v[50:51], v[36:37] op_sel_hi:[1,0,1]
	v_pk_fma_f32 v[34:35], v[148:149], v[50:51], v[34:35] op_sel_hi:[1,0,1]
	v_pk_fma_f32 v[32:33], v[150:151], v[52:53], v[32:33] op_sel_hi:[1,0,1]
	v_pk_fma_f32 v[30:31], v[148:149], v[52:53], v[30:31] op_sel_hi:[1,0,1]
	v_pk_fma_f32 v[28:29], v[150:151], v[54:55], v[28:29] op_sel_hi:[1,0,1]
	v_pk_fma_f32 v[26:27], v[148:149], v[54:55], v[26:27] op_sel_hi:[1,0,1]
	v_pk_fma_f32 v[24:25], v[150:151], v[56:57], v[24:25] op_sel_hi:[1,0,1]
	v_pk_fma_f32 v[22:23], v[148:149], v[56:57], v[22:23] op_sel_hi:[1,0,1]
	v_pk_fma_f32 v[20:21], v[150:151], v[58:59], v[20:21] op_sel_hi:[1,0,1]
	v_pk_fma_f32 v[18:19], v[148:149], v[58:59], v[18:19] op_sel_hi:[1,0,1]
	v_pk_fma_f32 v[16:17], v[150:151], v[60:61], v[16:17] op_sel_hi:[1,0,1]
	v_pk_fma_f32 v[14:15], v[148:149], v[60:61], v[14:15] op_sel_hi:[1,0,1]
	v_pk_fma_f32 v[12:13], v[150:151], v[62:63], v[12:13] op_sel_hi:[1,0,1]
	v_pk_fma_f32 v[10:11], v[148:149], v[62:63], v[10:11] op_sel_hi:[1,0,1]
	v_pk_fma_f32 v[8:9], v[150:151], v[64:65], v[8:9] op_sel_hi:[1,0,1]
	v_pk_fma_f32 v[6:7], v[148:149], v[64:65], v[6:7] op_sel_hi:[1,0,1]
	v_pk_fma_f32 v[4:5], v[150:151], v[66:67], v[4:5] op_sel_hi:[1,0,1]
	v_pk_fma_f32 v[2:3], v[148:149], v[66:67], v[2:3] op_sel_hi:[1,0,1]
	v_pk_fma_f32 v[36:37], v[154:155], v[50:51], v[36:37] op_sel:[0,1,0]
	v_pk_fma_f32 v[34:35], v[152:153], v[50:51], v[34:35] op_sel:[0,1,0]
	v_pk_fma_f32 v[32:33], v[154:155], v[52:53], v[32:33] op_sel:[0,1,0]
	v_pk_fma_f32 v[30:31], v[152:153], v[52:53], v[30:31] op_sel:[0,1,0]
	v_pk_fma_f32 v[28:29], v[154:155], v[54:55], v[28:29] op_sel:[0,1,0]
	v_pk_fma_f32 v[26:27], v[152:153], v[54:55], v[26:27] op_sel:[0,1,0]
	v_pk_fma_f32 v[24:25], v[154:155], v[56:57], v[24:25] op_sel:[0,1,0]
	v_pk_fma_f32 v[22:23], v[152:153], v[56:57], v[22:23] op_sel:[0,1,0]
	v_pk_fma_f32 v[20:21], v[154:155], v[58:59], v[20:21] op_sel:[0,1,0]
	v_pk_fma_f32 v[18:19], v[152:153], v[58:59], v[18:19] op_sel:[0,1,0]
	v_pk_fma_f32 v[16:17], v[154:155], v[60:61], v[16:17] op_sel:[0,1,0]
	v_pk_fma_f32 v[14:15], v[152:153], v[60:61], v[14:15] op_sel:[0,1,0]
	v_pk_fma_f32 v[12:13], v[154:155], v[62:63], v[12:13] op_sel:[0,1,0]
	v_pk_fma_f32 v[10:11], v[152:153], v[62:63], v[10:11] op_sel:[0,1,0]
	v_pk_fma_f32 v[8:9], v[154:155], v[64:65], v[8:9] op_sel:[0,1,0]
	v_pk_fma_f32 v[6:7], v[152:153], v[64:65], v[6:7] op_sel:[0,1,0]
	v_pk_fma_f32 v[4:5], v[154:155], v[66:67], v[4:5] op_sel:[0,1,0]
	v_pk_fma_f32 v[2:3], v[152:153], v[66:67], v[2:3] op_sel:[0,1,0]
	v_add_co_u32_e32 v204, vcc, s71, v40
	global_load_dwordx4 v[148:151], v[40:41], off
	v_addc_co_u32_e32 v205, vcc, 0, v41, vcc
	global_load_dwordx4 v[152:155], v[204:205], off
	v_lshl_add_u64 v[40:41], v[40:41], 0, s[14:15]
	v_add_u32_e32 v66, s9, v39
	ds_read2st64_b64 v[50:53], v66 offset1:8
	ds_read2st64_b64 v[54:57], v66 offset0:16 offset1:24
	ds_read2st64_b64 v[58:61], v66 offset0:32 offset1:40
	ds_read2st64_b64 v[62:65], v66 offset0:48 offset1:56
	ds_read_b64 v[66:67], v66 offset:32768
	s_add_i32 s9, s9, 8
	s_waitcnt vmcnt(14) lgkmcnt(0)
	v_pk_fma_f32 v[36:37], v[158:159], v[50:51], v[36:37] op_sel_hi:[1,0,1]
	v_pk_fma_f32 v[34:35], v[156:157], v[50:51], v[34:35] op_sel_hi:[1,0,1]
	v_pk_fma_f32 v[32:33], v[158:159], v[52:53], v[32:33] op_sel_hi:[1,0,1]
	v_pk_fma_f32 v[30:31], v[156:157], v[52:53], v[30:31] op_sel_hi:[1,0,1]
	v_pk_fma_f32 v[28:29], v[158:159], v[54:55], v[28:29] op_sel_hi:[1,0,1]
	v_pk_fma_f32 v[26:27], v[156:157], v[54:55], v[26:27] op_sel_hi:[1,0,1]
	v_pk_fma_f32 v[24:25], v[158:159], v[56:57], v[24:25] op_sel_hi:[1,0,1]
	v_pk_fma_f32 v[22:23], v[156:157], v[56:57], v[22:23] op_sel_hi:[1,0,1]
	v_pk_fma_f32 v[20:21], v[158:159], v[58:59], v[20:21] op_sel_hi:[1,0,1]
	v_pk_fma_f32 v[18:19], v[156:157], v[58:59], v[18:19] op_sel_hi:[1,0,1]
	v_pk_fma_f32 v[16:17], v[158:159], v[60:61], v[16:17] op_sel_hi:[1,0,1]
	v_pk_fma_f32 v[14:15], v[156:157], v[60:61], v[14:15] op_sel_hi:[1,0,1]
	v_pk_fma_f32 v[12:13], v[158:159], v[62:63], v[12:13] op_sel_hi:[1,0,1]
	v_pk_fma_f32 v[10:11], v[156:157], v[62:63], v[10:11] op_sel_hi:[1,0,1]
	v_pk_fma_f32 v[8:9], v[158:159], v[64:65], v[8:9] op_sel_hi:[1,0,1]
	v_pk_fma_f32 v[6:7], v[156:157], v[64:65], v[6:7] op_sel_hi:[1,0,1]
	v_pk_fma_f32 v[4:5], v[158:159], v[66:67], v[4:5] op_sel_hi:[1,0,1]
	v_pk_fma_f32 v[2:3], v[156:157], v[66:67], v[2:3] op_sel_hi:[1,0,1]
	v_pk_fma_f32 v[36:37], v[162:163], v[50:51], v[36:37] op_sel:[0,1,0]
	v_pk_fma_f32 v[34:35], v[160:161], v[50:51], v[34:35] op_sel:[0,1,0]
	v_pk_fma_f32 v[32:33], v[162:163], v[52:53], v[32:33] op_sel:[0,1,0]
	v_pk_fma_f32 v[30:31], v[160:161], v[52:53], v[30:31] op_sel:[0,1,0]
	v_pk_fma_f32 v[28:29], v[162:163], v[54:55], v[28:29] op_sel:[0,1,0]
	v_pk_fma_f32 v[26:27], v[160:161], v[54:55], v[26:27] op_sel:[0,1,0]
	v_pk_fma_f32 v[24:25], v[162:163], v[56:57], v[24:25] op_sel:[0,1,0]
	v_pk_fma_f32 v[22:23], v[160:161], v[56:57], v[22:23] op_sel:[0,1,0]
	v_pk_fma_f32 v[20:21], v[162:163], v[58:59], v[20:21] op_sel:[0,1,0]
	v_pk_fma_f32 v[18:19], v[160:161], v[58:59], v[18:19] op_sel:[0,1,0]
	v_pk_fma_f32 v[16:17], v[162:163], v[60:61], v[16:17] op_sel:[0,1,0]
	v_pk_fma_f32 v[14:15], v[160:161], v[60:61], v[14:15] op_sel:[0,1,0]
	v_pk_fma_f32 v[12:13], v[162:163], v[62:63], v[12:13] op_sel:[0,1,0]
	v_pk_fma_f32 v[10:11], v[160:161], v[62:63], v[10:11] op_sel:[0,1,0]
	v_pk_fma_f32 v[8:9], v[162:163], v[64:65], v[8:9] op_sel:[0,1,0]
	v_pk_fma_f32 v[6:7], v[160:161], v[64:65], v[6:7] op_sel:[0,1,0]
	v_pk_fma_f32 v[4:5], v[162:163], v[66:67], v[4:5] op_sel:[0,1,0]
	v_pk_fma_f32 v[2:3], v[160:161], v[66:67], v[2:3] op_sel:[0,1,0]
	v_add_co_u32_e32 v204, vcc, s71, v40
	global_load_dwordx4 v[156:159], v[40:41], off
	v_addc_co_u32_e32 v205, vcc, 0, v41, vcc
	global_load_dwordx4 v[160:163], v[204:205], off
	v_lshl_add_u64 v[40:41], v[40:41], 0, s[14:15]
	v_add_u32_e32 v66, s9, v39
	ds_read2st64_b64 v[50:53], v66 offset1:8
	ds_read2st64_b64 v[54:57], v66 offset0:16 offset1:24
	ds_read2st64_b64 v[58:61], v66 offset0:32 offset1:40
	ds_read2st64_b64 v[62:65], v66 offset0:48 offset1:56
	ds_read_b64 v[66:67], v66 offset:32768
	s_add_i32 s9, s9, 8
	s_waitcnt vmcnt(14) lgkmcnt(0)
	v_pk_fma_f32 v[36:37], v[166:167], v[50:51], v[36:37] op_sel_hi:[1,0,1]
	v_pk_fma_f32 v[34:35], v[164:165], v[50:51], v[34:35] op_sel_hi:[1,0,1]
	v_pk_fma_f32 v[32:33], v[166:167], v[52:53], v[32:33] op_sel_hi:[1,0,1]
	v_pk_fma_f32 v[30:31], v[164:165], v[52:53], v[30:31] op_sel_hi:[1,0,1]
	v_pk_fma_f32 v[28:29], v[166:167], v[54:55], v[28:29] op_sel_hi:[1,0,1]
	v_pk_fma_f32 v[26:27], v[164:165], v[54:55], v[26:27] op_sel_hi:[1,0,1]
	v_pk_fma_f32 v[24:25], v[166:167], v[56:57], v[24:25] op_sel_hi:[1,0,1]
	v_pk_fma_f32 v[22:23], v[164:165], v[56:57], v[22:23] op_sel_hi:[1,0,1]
	v_pk_fma_f32 v[20:21], v[166:167], v[58:59], v[20:21] op_sel_hi:[1,0,1]
	v_pk_fma_f32 v[18:19], v[164:165], v[58:59], v[18:19] op_sel_hi:[1,0,1]
	v_pk_fma_f32 v[16:17], v[166:167], v[60:61], v[16:17] op_sel_hi:[1,0,1]
	v_pk_fma_f32 v[14:15], v[164:165], v[60:61], v[14:15] op_sel_hi:[1,0,1]
	v_pk_fma_f32 v[12:13], v[166:167], v[62:63], v[12:13] op_sel_hi:[1,0,1]
	v_pk_fma_f32 v[10:11], v[164:165], v[62:63], v[10:11] op_sel_hi:[1,0,1]
	v_pk_fma_f32 v[8:9], v[166:167], v[64:65], v[8:9] op_sel_hi:[1,0,1]
	v_pk_fma_f32 v[6:7], v[164:165], v[64:65], v[6:7] op_sel_hi:[1,0,1]
	v_pk_fma_f32 v[4:5], v[166:167], v[66:67], v[4:5] op_sel_hi:[1,0,1]
	v_pk_fma_f32 v[2:3], v[164:165], v[66:67], v[2:3] op_sel_hi:[1,0,1]
	v_pk_fma_f32 v[36:37], v[170:171], v[50:51], v[36:37] op_sel:[0,1,0]
	v_pk_fma_f32 v[34:35], v[168:169], v[50:51], v[34:35] op_sel:[0,1,0]
	v_pk_fma_f32 v[32:33], v[170:171], v[52:53], v[32:33] op_sel:[0,1,0]
	v_pk_fma_f32 v[30:31], v[168:169], v[52:53], v[30:31] op_sel:[0,1,0]
	v_pk_fma_f32 v[28:29], v[170:171], v[54:55], v[28:29] op_sel:[0,1,0]
	v_pk_fma_f32 v[26:27], v[168:169], v[54:55], v[26:27] op_sel:[0,1,0]
	v_pk_fma_f32 v[24:25], v[170:171], v[56:57], v[24:25] op_sel:[0,1,0]
	v_pk_fma_f32 v[22:23], v[168:169], v[56:57], v[22:23] op_sel:[0,1,0]
	v_pk_fma_f32 v[20:21], v[170:171], v[58:59], v[20:21] op_sel:[0,1,0]
	v_pk_fma_f32 v[18:19], v[168:169], v[58:59], v[18:19] op_sel:[0,1,0]
	v_pk_fma_f32 v[16:17], v[170:171], v[60:61], v[16:17] op_sel:[0,1,0]
	v_pk_fma_f32 v[14:15], v[168:169], v[60:61], v[14:15] op_sel:[0,1,0]
	v_pk_fma_f32 v[12:13], v[170:171], v[62:63], v[12:13] op_sel:[0,1,0]
	v_pk_fma_f32 v[10:11], v[168:169], v[62:63], v[10:11] op_sel:[0,1,0]
	v_pk_fma_f32 v[8:9], v[170:171], v[64:65], v[8:9] op_sel:[0,1,0]
	v_pk_fma_f32 v[6:7], v[168:169], v[64:65], v[6:7] op_sel:[0,1,0]
	v_pk_fma_f32 v[4:5], v[170:171], v[66:67], v[4:5] op_sel:[0,1,0]
	v_pk_fma_f32 v[2:3], v[168:169], v[66:67], v[2:3] op_sel:[0,1,0]
	v_add_co_u32_e32 v204, vcc, s71, v40
	global_load_dwordx4 v[164:167], v[40:41], off
	v_addc_co_u32_e32 v205, vcc, 0, v41, vcc
	global_load_dwordx4 v[168:171], v[204:205], off
	v_lshl_add_u64 v[40:41], v[40:41], 0, s[14:15]
	v_add_u32_e32 v66, s9, v39
	ds_read2st64_b64 v[50:53], v66 offset1:8
	ds_read2st64_b64 v[54:57], v66 offset0:16 offset1:24
	ds_read2st64_b64 v[58:61], v66 offset0:32 offset1:40
	ds_read2st64_b64 v[62:65], v66 offset0:48 offset1:56
	ds_read_b64 v[66:67], v66 offset:32768
	s_add_i32 s9, s9, 8
	s_waitcnt vmcnt(14) lgkmcnt(0)
	v_pk_fma_f32 v[36:37], v[174:175], v[50:51], v[36:37] op_sel_hi:[1,0,1]
	v_pk_fma_f32 v[34:35], v[172:173], v[50:51], v[34:35] op_sel_hi:[1,0,1]
	v_pk_fma_f32 v[32:33], v[174:175], v[52:53], v[32:33] op_sel_hi:[1,0,1]
	v_pk_fma_f32 v[30:31], v[172:173], v[52:53], v[30:31] op_sel_hi:[1,0,1]
	v_pk_fma_f32 v[28:29], v[174:175], v[54:55], v[28:29] op_sel_hi:[1,0,1]
	v_pk_fma_f32 v[26:27], v[172:173], v[54:55], v[26:27] op_sel_hi:[1,0,1]
	v_pk_fma_f32 v[24:25], v[174:175], v[56:57], v[24:25] op_sel_hi:[1,0,1]
	v_pk_fma_f32 v[22:23], v[172:173], v[56:57], v[22:23] op_sel_hi:[1,0,1]
	v_pk_fma_f32 v[20:21], v[174:175], v[58:59], v[20:21] op_sel_hi:[1,0,1]
	v_pk_fma_f32 v[18:19], v[172:173], v[58:59], v[18:19] op_sel_hi:[1,0,1]
	v_pk_fma_f32 v[16:17], v[174:175], v[60:61], v[16:17] op_sel_hi:[1,0,1]
	v_pk_fma_f32 v[14:15], v[172:173], v[60:61], v[14:15] op_sel_hi:[1,0,1]
	v_pk_fma_f32 v[12:13], v[174:175], v[62:63], v[12:13] op_sel_hi:[1,0,1]
	v_pk_fma_f32 v[10:11], v[172:173], v[62:63], v[10:11] op_sel_hi:[1,0,1]
	v_pk_fma_f32 v[8:9], v[174:175], v[64:65], v[8:9] op_sel_hi:[1,0,1]
	v_pk_fma_f32 v[6:7], v[172:173], v[64:65], v[6:7] op_sel_hi:[1,0,1]
	v_pk_fma_f32 v[4:5], v[174:175], v[66:67], v[4:5] op_sel_hi:[1,0,1]
	v_pk_fma_f32 v[2:3], v[172:173], v[66:67], v[2:3] op_sel_hi:[1,0,1]
	v_pk_fma_f32 v[36:37], v[178:179], v[50:51], v[36:37] op_sel:[0,1,0]
	v_pk_fma_f32 v[34:35], v[176:177], v[50:51], v[34:35] op_sel:[0,1,0]
	v_pk_fma_f32 v[32:33], v[178:179], v[52:53], v[32:33] op_sel:[0,1,0]
	v_pk_fma_f32 v[30:31], v[176:177], v[52:53], v[30:31] op_sel:[0,1,0]
	v_pk_fma_f32 v[28:29], v[178:179], v[54:55], v[28:29] op_sel:[0,1,0]
	v_pk_fma_f32 v[26:27], v[176:177], v[54:55], v[26:27] op_sel:[0,1,0]
	v_pk_fma_f32 v[24:25], v[178:179], v[56:57], v[24:25] op_sel:[0,1,0]
	v_pk_fma_f32 v[22:23], v[176:177], v[56:57], v[22:23] op_sel:[0,1,0]
	v_pk_fma_f32 v[20:21], v[178:179], v[58:59], v[20:21] op_sel:[0,1,0]
	v_pk_fma_f32 v[18:19], v[176:177], v[58:59], v[18:19] op_sel:[0,1,0]
	v_pk_fma_f32 v[16:17], v[178:179], v[60:61], v[16:17] op_sel:[0,1,0]
	v_pk_fma_f32 v[14:15], v[176:177], v[60:61], v[14:15] op_sel:[0,1,0]
	v_pk_fma_f32 v[12:13], v[178:179], v[62:63], v[12:13] op_sel:[0,1,0]
	v_pk_fma_f32 v[10:11], v[176:177], v[62:63], v[10:11] op_sel:[0,1,0]
	v_pk_fma_f32 v[8:9], v[178:179], v[64:65], v[8:9] op_sel:[0,1,0]
	v_pk_fma_f32 v[6:7], v[176:177], v[64:65], v[6:7] op_sel:[0,1,0]
	v_pk_fma_f32 v[4:5], v[178:179], v[66:67], v[4:5] op_sel:[0,1,0]
	v_pk_fma_f32 v[2:3], v[176:177], v[66:67], v[2:3] op_sel:[0,1,0]
	v_add_co_u32_e32 v204, vcc, s71, v40
	global_load_dwordx4 v[172:175], v[40:41], off
	v_addc_co_u32_e32 v205, vcc, 0, v41, vcc
	global_load_dwordx4 v[176:179], v[204:205], off
	v_lshl_add_u64 v[40:41], v[40:41], 0, s[14:15]
	v_add_u32_e32 v66, s9, v39
	ds_read2st64_b64 v[50:53], v66 offset1:8
	ds_read2st64_b64 v[54:57], v66 offset0:16 offset1:24
	ds_read2st64_b64 v[58:61], v66 offset0:32 offset1:40
	ds_read2st64_b64 v[62:65], v66 offset0:48 offset1:56
	ds_read_b64 v[66:67], v66 offset:32768
	s_add_i32 s9, s9, 8
	s_waitcnt vmcnt(14) lgkmcnt(0)
	v_pk_fma_f32 v[36:37], v[182:183], v[50:51], v[36:37] op_sel_hi:[1,0,1]
	v_pk_fma_f32 v[34:35], v[180:181], v[50:51], v[34:35] op_sel_hi:[1,0,1]
	v_pk_fma_f32 v[32:33], v[182:183], v[52:53], v[32:33] op_sel_hi:[1,0,1]
	v_pk_fma_f32 v[30:31], v[180:181], v[52:53], v[30:31] op_sel_hi:[1,0,1]
	v_pk_fma_f32 v[28:29], v[182:183], v[54:55], v[28:29] op_sel_hi:[1,0,1]
	v_pk_fma_f32 v[26:27], v[180:181], v[54:55], v[26:27] op_sel_hi:[1,0,1]
	v_pk_fma_f32 v[24:25], v[182:183], v[56:57], v[24:25] op_sel_hi:[1,0,1]
	v_pk_fma_f32 v[22:23], v[180:181], v[56:57], v[22:23] op_sel_hi:[1,0,1]
	v_pk_fma_f32 v[20:21], v[182:183], v[58:59], v[20:21] op_sel_hi:[1,0,1]
	v_pk_fma_f32 v[18:19], v[180:181], v[58:59], v[18:19] op_sel_hi:[1,0,1]
	v_pk_fma_f32 v[16:17], v[182:183], v[60:61], v[16:17] op_sel_hi:[1,0,1]
	v_pk_fma_f32 v[14:15], v[180:181], v[60:61], v[14:15] op_sel_hi:[1,0,1]
	v_pk_fma_f32 v[12:13], v[182:183], v[62:63], v[12:13] op_sel_hi:[1,0,1]
	v_pk_fma_f32 v[10:11], v[180:181], v[62:63], v[10:11] op_sel_hi:[1,0,1]
	v_pk_fma_f32 v[8:9], v[182:183], v[64:65], v[8:9] op_sel_hi:[1,0,1]
	v_pk_fma_f32 v[6:7], v[180:181], v[64:65], v[6:7] op_sel_hi:[1,0,1]
	v_pk_fma_f32 v[4:5], v[182:183], v[66:67], v[4:5] op_sel_hi:[1,0,1]
	v_pk_fma_f32 v[2:3], v[180:181], v[66:67], v[2:3] op_sel_hi:[1,0,1]
	v_pk_fma_f32 v[36:37], v[186:187], v[50:51], v[36:37] op_sel:[0,1,0]
	v_pk_fma_f32 v[34:35], v[184:185], v[50:51], v[34:35] op_sel:[0,1,0]
	v_pk_fma_f32 v[32:33], v[186:187], v[52:53], v[32:33] op_sel:[0,1,0]
	v_pk_fma_f32 v[30:31], v[184:185], v[52:53], v[30:31] op_sel:[0,1,0]
	v_pk_fma_f32 v[28:29], v[186:187], v[54:55], v[28:29] op_sel:[0,1,0]
	v_pk_fma_f32 v[26:27], v[184:185], v[54:55], v[26:27] op_sel:[0,1,0]
	v_pk_fma_f32 v[24:25], v[186:187], v[56:57], v[24:25] op_sel:[0,1,0]
	v_pk_fma_f32 v[22:23], v[184:185], v[56:57], v[22:23] op_sel:[0,1,0]
	v_pk_fma_f32 v[20:21], v[186:187], v[58:59], v[20:21] op_sel:[0,1,0]
	v_pk_fma_f32 v[18:19], v[184:185], v[58:59], v[18:19] op_sel:[0,1,0]
	v_pk_fma_f32 v[16:17], v[186:187], v[60:61], v[16:17] op_sel:[0,1,0]
	v_pk_fma_f32 v[14:15], v[184:185], v[60:61], v[14:15] op_sel:[0,1,0]
	v_pk_fma_f32 v[12:13], v[186:187], v[62:63], v[12:13] op_sel:[0,1,0]
	v_pk_fma_f32 v[10:11], v[184:185], v[62:63], v[10:11] op_sel:[0,1,0]
	v_pk_fma_f32 v[8:9], v[186:187], v[64:65], v[8:9] op_sel:[0,1,0]
	v_pk_fma_f32 v[6:7], v[184:185], v[64:65], v[6:7] op_sel:[0,1,0]
	v_pk_fma_f32 v[4:5], v[186:187], v[66:67], v[4:5] op_sel:[0,1,0]
	v_pk_fma_f32 v[2:3], v[184:185], v[66:67], v[2:3] op_sel:[0,1,0]
	v_add_co_u32_e32 v204, vcc, s71, v40
	global_load_dwordx4 v[180:183], v[40:41], off
	v_addc_co_u32_e32 v205, vcc, 0, v41, vcc
	global_load_dwordx4 v[184:187], v[204:205], off
	v_lshl_add_u64 v[40:41], v[40:41], 0, s[14:15]
	v_add_u32_e32 v66, s9, v39
	ds_read2st64_b64 v[50:53], v66 offset1:8
	ds_read2st64_b64 v[54:57], v66 offset0:16 offset1:24
	ds_read2st64_b64 v[58:61], v66 offset0:32 offset1:40
	ds_read2st64_b64 v[62:65], v66 offset0:48 offset1:56
	ds_read_b64 v[66:67], v66 offset:32768
	s_add_i32 s9, s9, 8
	s_waitcnt vmcnt(14) lgkmcnt(0)
	v_pk_fma_f32 v[36:37], v[190:191], v[50:51], v[36:37] op_sel_hi:[1,0,1]
	v_pk_fma_f32 v[34:35], v[188:189], v[50:51], v[34:35] op_sel_hi:[1,0,1]
	v_pk_fma_f32 v[32:33], v[190:191], v[52:53], v[32:33] op_sel_hi:[1,0,1]
	v_pk_fma_f32 v[30:31], v[188:189], v[52:53], v[30:31] op_sel_hi:[1,0,1]
	v_pk_fma_f32 v[28:29], v[190:191], v[54:55], v[28:29] op_sel_hi:[1,0,1]
	v_pk_fma_f32 v[26:27], v[188:189], v[54:55], v[26:27] op_sel_hi:[1,0,1]
	v_pk_fma_f32 v[24:25], v[190:191], v[56:57], v[24:25] op_sel_hi:[1,0,1]
	v_pk_fma_f32 v[22:23], v[188:189], v[56:57], v[22:23] op_sel_hi:[1,0,1]
	v_pk_fma_f32 v[20:21], v[190:191], v[58:59], v[20:21] op_sel_hi:[1,0,1]
	v_pk_fma_f32 v[18:19], v[188:189], v[58:59], v[18:19] op_sel_hi:[1,0,1]
	v_pk_fma_f32 v[16:17], v[190:191], v[60:61], v[16:17] op_sel_hi:[1,0,1]
	v_pk_fma_f32 v[14:15], v[188:189], v[60:61], v[14:15] op_sel_hi:[1,0,1]
	v_pk_fma_f32 v[12:13], v[190:191], v[62:63], v[12:13] op_sel_hi:[1,0,1]
	v_pk_fma_f32 v[10:11], v[188:189], v[62:63], v[10:11] op_sel_hi:[1,0,1]
	v_pk_fma_f32 v[8:9], v[190:191], v[64:65], v[8:9] op_sel_hi:[1,0,1]
	v_pk_fma_f32 v[6:7], v[188:189], v[64:65], v[6:7] op_sel_hi:[1,0,1]
	v_pk_fma_f32 v[4:5], v[190:191], v[66:67], v[4:5] op_sel_hi:[1,0,1]
	v_pk_fma_f32 v[2:3], v[188:189], v[66:67], v[2:3] op_sel_hi:[1,0,1]
	v_pk_fma_f32 v[36:37], v[194:195], v[50:51], v[36:37] op_sel:[0,1,0]
	v_pk_fma_f32 v[34:35], v[192:193], v[50:51], v[34:35] op_sel:[0,1,0]
	v_pk_fma_f32 v[32:33], v[194:195], v[52:53], v[32:33] op_sel:[0,1,0]
	v_pk_fma_f32 v[30:31], v[192:193], v[52:53], v[30:31] op_sel:[0,1,0]
	v_pk_fma_f32 v[28:29], v[194:195], v[54:55], v[28:29] op_sel:[0,1,0]
	v_pk_fma_f32 v[26:27], v[192:193], v[54:55], v[26:27] op_sel:[0,1,0]
	v_pk_fma_f32 v[24:25], v[194:195], v[56:57], v[24:25] op_sel:[0,1,0]
	v_pk_fma_f32 v[22:23], v[192:193], v[56:57], v[22:23] op_sel:[0,1,0]
	v_pk_fma_f32 v[20:21], v[194:195], v[58:59], v[20:21] op_sel:[0,1,0]
	v_pk_fma_f32 v[18:19], v[192:193], v[58:59], v[18:19] op_sel:[0,1,0]
	v_pk_fma_f32 v[16:17], v[194:195], v[60:61], v[16:17] op_sel:[0,1,0]
	v_pk_fma_f32 v[14:15], v[192:193], v[60:61], v[14:15] op_sel:[0,1,0]
	v_pk_fma_f32 v[12:13], v[194:195], v[62:63], v[12:13] op_sel:[0,1,0]
	v_pk_fma_f32 v[10:11], v[192:193], v[62:63], v[10:11] op_sel:[0,1,0]
	v_pk_fma_f32 v[8:9], v[194:195], v[64:65], v[8:9] op_sel:[0,1,0]
	v_pk_fma_f32 v[6:7], v[192:193], v[64:65], v[6:7] op_sel:[0,1,0]
	v_pk_fma_f32 v[4:5], v[194:195], v[66:67], v[4:5] op_sel:[0,1,0]
	v_pk_fma_f32 v[2:3], v[192:193], v[66:67], v[2:3] op_sel:[0,1,0]
	v_add_co_u32_e32 v204, vcc, s71, v40
	global_load_dwordx4 v[188:191], v[40:41], off
	v_addc_co_u32_e32 v205, vcc, 0, v41, vcc
	global_load_dwordx4 v[192:195], v[204:205], off
	v_lshl_add_u64 v[40:41], v[40:41], 0, s[14:15]
	v_add_u32_e32 v66, s9, v39
	ds_read2st64_b64 v[50:53], v66 offset1:8
	ds_read2st64_b64 v[54:57], v66 offset0:16 offset1:24
	ds_read2st64_b64 v[58:61], v66 offset0:32 offset1:40
	ds_read2st64_b64 v[62:65], v66 offset0:48 offset1:56
	ds_read_b64 v[66:67], v66 offset:32768
	s_add_i32 s9, s9, 8
	s_waitcnt vmcnt(14) lgkmcnt(0)
	v_pk_fma_f32 v[36:37], v[198:199], v[50:51], v[36:37] op_sel_hi:[1,0,1]
	v_pk_fma_f32 v[34:35], v[196:197], v[50:51], v[34:35] op_sel_hi:[1,0,1]
	v_pk_fma_f32 v[32:33], v[198:199], v[52:53], v[32:33] op_sel_hi:[1,0,1]
	v_pk_fma_f32 v[30:31], v[196:197], v[52:53], v[30:31] op_sel_hi:[1,0,1]
	v_pk_fma_f32 v[28:29], v[198:199], v[54:55], v[28:29] op_sel_hi:[1,0,1]
	v_pk_fma_f32 v[26:27], v[196:197], v[54:55], v[26:27] op_sel_hi:[1,0,1]
	v_pk_fma_f32 v[24:25], v[198:199], v[56:57], v[24:25] op_sel_hi:[1,0,1]
	v_pk_fma_f32 v[22:23], v[196:197], v[56:57], v[22:23] op_sel_hi:[1,0,1]
	v_pk_fma_f32 v[20:21], v[198:199], v[58:59], v[20:21] op_sel_hi:[1,0,1]
	v_pk_fma_f32 v[18:19], v[196:197], v[58:59], v[18:19] op_sel_hi:[1,0,1]
	v_pk_fma_f32 v[16:17], v[198:199], v[60:61], v[16:17] op_sel_hi:[1,0,1]
	v_pk_fma_f32 v[14:15], v[196:197], v[60:61], v[14:15] op_sel_hi:[1,0,1]
	v_pk_fma_f32 v[12:13], v[198:199], v[62:63], v[12:13] op_sel_hi:[1,0,1]
	v_pk_fma_f32 v[10:11], v[196:197], v[62:63], v[10:11] op_sel_hi:[1,0,1]
	v_pk_fma_f32 v[8:9], v[198:199], v[64:65], v[8:9] op_sel_hi:[1,0,1]
	v_pk_fma_f32 v[6:7], v[196:197], v[64:65], v[6:7] op_sel_hi:[1,0,1]
	v_pk_fma_f32 v[4:5], v[198:199], v[66:67], v[4:5] op_sel_hi:[1,0,1]
	v_pk_fma_f32 v[2:3], v[196:197], v[66:67], v[2:3] op_sel_hi:[1,0,1]
	v_pk_fma_f32 v[36:37], v[202:203], v[50:51], v[36:37] op_sel:[0,1,0]
	v_pk_fma_f32 v[34:35], v[200:201], v[50:51], v[34:35] op_sel:[0,1,0]
	v_pk_fma_f32 v[32:33], v[202:203], v[52:53], v[32:33] op_sel:[0,1,0]
	v_pk_fma_f32 v[30:31], v[200:201], v[52:53], v[30:31] op_sel:[0,1,0]
	v_pk_fma_f32 v[28:29], v[202:203], v[54:55], v[28:29] op_sel:[0,1,0]
	v_pk_fma_f32 v[26:27], v[200:201], v[54:55], v[26:27] op_sel:[0,1,0]
	v_pk_fma_f32 v[24:25], v[202:203], v[56:57], v[24:25] op_sel:[0,1,0]
	v_pk_fma_f32 v[22:23], v[200:201], v[56:57], v[22:23] op_sel:[0,1,0]
	v_pk_fma_f32 v[20:21], v[202:203], v[58:59], v[20:21] op_sel:[0,1,0]
	v_pk_fma_f32 v[18:19], v[200:201], v[58:59], v[18:19] op_sel:[0,1,0]
	v_pk_fma_f32 v[16:17], v[202:203], v[60:61], v[16:17] op_sel:[0,1,0]
	v_pk_fma_f32 v[14:15], v[200:201], v[60:61], v[14:15] op_sel:[0,1,0]
	v_pk_fma_f32 v[12:13], v[202:203], v[62:63], v[12:13] op_sel:[0,1,0]
	v_pk_fma_f32 v[10:11], v[200:201], v[62:63], v[10:11] op_sel:[0,1,0]
	v_pk_fma_f32 v[8:9], v[202:203], v[64:65], v[8:9] op_sel:[0,1,0]
	v_pk_fma_f32 v[6:7], v[200:201], v[64:65], v[6:7] op_sel:[0,1,0]
	v_pk_fma_f32 v[4:5], v[202:203], v[66:67], v[4:5] op_sel:[0,1,0]
	v_pk_fma_f32 v[2:3], v[200:201], v[66:67], v[2:3] op_sel:[0,1,0]
	v_add_co_u32_e32 v204, vcc, s71, v40
	global_load_dwordx4 v[196:199], v[40:41], off
	v_addc_co_u32_e32 v205, vcc, 0, v41, vcc
	global_load_dwordx4 v[200:203], v[204:205], off
	v_lshl_add_u64 v[40:41], v[40:41], 0, s[14:15]
	s_sub_u32 s100, s100, 1
	s_cmp_lg_u32 s100, 0
	s_cbranch_scc1 .Lmod_trip
	v_add_u32_e32 v66, s9, v39
	ds_read2st64_b64 v[50:53], v66 offset1:8
	ds_read2st64_b64 v[54:57], v66 offset0:16 offset1:24
	ds_read2st64_b64 v[58:61], v66 offset0:32 offset1:40
	ds_read2st64_b64 v[62:65], v66 offset0:48 offset1:56
	ds_read_b64 v[66:67], v66 offset:32768
	s_add_i32 s9, s9, 8
	s_waitcnt vmcnt(14) lgkmcnt(0)
	v_pk_fma_f32 v[36:37], v[142:143], v[50:51], v[36:37] op_sel_hi:[1,0,1]
	v_pk_fma_f32 v[34:35], v[140:141], v[50:51], v[34:35] op_sel_hi:[1,0,1]
	v_pk_fma_f32 v[32:33], v[142:143], v[52:53], v[32:33] op_sel_hi:[1,0,1]
	v_pk_fma_f32 v[30:31], v[140:141], v[52:53], v[30:31] op_sel_hi:[1,0,1]
	v_pk_fma_f32 v[28:29], v[142:143], v[54:55], v[28:29] op_sel_hi:[1,0,1]
	v_pk_fma_f32 v[26:27], v[140:141], v[54:55], v[26:27] op_sel_hi:[1,0,1]
	v_pk_fma_f32 v[24:25], v[142:143], v[56:57], v[24:25] op_sel_hi:[1,0,1]
	v_pk_fma_f32 v[22:23], v[140:141], v[56:57], v[22:23] op_sel_hi:[1,0,1]
	v_pk_fma_f32 v[20:21], v[142:143], v[58:59], v[20:21] op_sel_hi:[1,0,1]
	v_pk_fma_f32 v[18:19], v[140:141], v[58:59], v[18:19] op_sel_hi:[1,0,1]
	v_pk_fma_f32 v[16:17], v[142:143], v[60:61], v[16:17] op_sel_hi:[1,0,1]
	v_pk_fma_f32 v[14:15], v[140:141], v[60:61], v[14:15] op_sel_hi:[1,0,1]
	v_pk_fma_f32 v[12:13], v[142:143], v[62:63], v[12:13] op_sel_hi:[1,0,1]
	v_pk_fma_f32 v[10:11], v[140:141], v[62:63], v[10:11] op_sel_hi:[1,0,1]
	v_pk_fma_f32 v[8:9], v[142:143], v[64:65], v[8:9] op_sel_hi:[1,0,1]
	v_pk_fma_f32 v[6:7], v[140:141], v[64:65], v[6:7] op_sel_hi:[1,0,1]
	v_pk_fma_f32 v[4:5], v[142:143], v[66:67], v[4:5] op_sel_hi:[1,0,1]
	v_pk_fma_f32 v[2:3], v[140:141], v[66:67], v[2:3] op_sel_hi:[1,0,1]
	v_pk_fma_f32 v[36:37], v[146:147], v[50:51], v[36:37] op_sel:[0,1,0]
	v_pk_fma_f32 v[34:35], v[144:145], v[50:51], v[34:35] op_sel:[0,1,0]
	v_pk_fma_f32 v[32:33], v[146:147], v[52:53], v[32:33] op_sel:[0,1,0]
	v_pk_fma_f32 v[30:31], v[144:145], v[52:53], v[30:31] op_sel:[0,1,0]
	v_pk_fma_f32 v[28:29], v[146:147], v[54:55], v[28:29] op_sel:[0,1,0]
	v_pk_fma_f32 v[26:27], v[144:145], v[54:55], v[26:27] op_sel:[0,1,0]
	v_pk_fma_f32 v[24:25], v[146:147], v[56:57], v[24:25] op_sel:[0,1,0]
	v_pk_fma_f32 v[22:23], v[144:145], v[56:57], v[22:23] op_sel:[0,1,0]
	v_pk_fma_f32 v[20:21], v[146:147], v[58:59], v[20:21] op_sel:[0,1,0]
	v_pk_fma_f32 v[18:19], v[144:145], v[58:59], v[18:19] op_sel:[0,1,0]
	v_pk_fma_f32 v[16:17], v[146:147], v[60:61], v[16:17] op_sel:[0,1,0]
	v_pk_fma_f32 v[14:15], v[144:145], v[60:61], v[14:15] op_sel:[0,1,0]
	v_pk_fma_f32 v[12:13], v[146:147], v[62:63], v[12:13] op_sel:[0,1,0]
	v_pk_fma_f32 v[10:11], v[144:145], v[62:63], v[10:11] op_sel:[0,1,0]
	v_pk_fma_f32 v[8:9], v[146:147], v[64:65], v[8:9] op_sel:[0,1,0]
	v_pk_fma_f32 v[6:7], v[144:145], v[64:65], v[6:7] op_sel:[0,1,0]
	v_pk_fma_f32 v[4:5], v[146:147], v[66:67], v[4:5] op_sel:[0,1,0]
	v_pk_fma_f32 v[2:3], v[144:145], v[66:67], v[2:3] op_sel:[0,1,0]
	v_add_u32_e32 v66, s9, v39
	ds_read2st64_b64 v[50:53], v66 offset1:8
	ds_read2st64_b64 v[54:57], v66 offset0:16 offset1:24
	ds_read2st64_b64 v[58:61], v66 offset0:32 offset1:40
	ds_read2st64_b64 v[62:65], v66 offset0:48 offset1:56
	ds_read_b64 v[66:67], v66 offset:32768
	s_add_i32 s9, s9, 8
	s_waitcnt vmcnt(12) lgkmcnt(0)
	v_pk_fma_f32 v[36:37], v[150:151], v[50:51], v[36:37] op_sel_hi:[1,0,1]
	v_pk_fma_f32 v[34:35], v[148:149], v[50:51], v[34:35] op_sel_hi:[1,0,1]
	v_pk_fma_f32 v[32:33], v[150:151], v[52:53], v[32:33] op_sel_hi:[1,0,1]
	v_pk_fma_f32 v[30:31], v[148:149], v[52:53], v[30:31] op_sel_hi:[1,0,1]
	v_pk_fma_f32 v[28:29], v[150:151], v[54:55], v[28:29] op_sel_hi:[1,0,1]
	v_pk_fma_f32 v[26:27], v[148:149], v[54:55], v[26:27] op_sel_hi:[1,0,1]
	v_pk_fma_f32 v[24:25], v[150:151], v[56:57], v[24:25] op_sel_hi:[1,0,1]
	v_pk_fma_f32 v[22:23], v[148:149], v[56:57], v[22:23] op_sel_hi:[1,0,1]
	v_pk_fma_f32 v[20:21], v[150:151], v[58:59], v[20:21] op_sel_hi:[1,0,1]
	v_pk_fma_f32 v[18:19], v[148:149], v[58:59], v[18:19] op_sel_hi:[1,0,1]
	v_pk_fma_f32 v[16:17], v[150:151], v[60:61], v[16:17] op_sel_hi:[1,0,1]
	v_pk_fma_f32 v[14:15], v[148:149], v[60:61], v[14:15] op_sel_hi:[1,0,1]
	v_pk_fma_f32 v[12:13], v[150:151], v[62:63], v[12:13] op_sel_hi:[1,0,1]
	v_pk_fma_f32 v[10:11], v[148:149], v[62:63], v[10:11] op_sel_hi:[1,0,1]
	v_pk_fma_f32 v[8:9], v[150:151], v[64:65], v[8:9] op_sel_hi:[1,0,1]
	v_pk_fma_f32 v[6:7], v[148:149], v[64:65], v[6:7] op_sel_hi:[1,0,1]
	v_pk_fma_f32 v[4:5], v[150:151], v[66:67], v[4:5] op_sel_hi:[1,0,1]
	v_pk_fma_f32 v[2:3], v[148:149], v[66:67], v[2:3] op_sel_hi:[1,0,1]
	v_pk_fma_f32 v[36:37], v[154:155], v[50:51], v[36:37] op_sel:[0,1,0]
	v_pk_fma_f32 v[34:35], v[152:153], v[50:51], v[34:35] op_sel:[0,1,0]
	v_pk_fma_f32 v[32:33], v[154:155], v[52:53], v[32:33] op_sel:[0,1,0]
	v_pk_fma_f32 v[30:31], v[152:153], v[52:53], v[30:31] op_sel:[0,1,0]
	v_pk_fma_f32 v[28:29], v[154:155], v[54:55], v[28:29] op_sel:[0,1,0]
	v_pk_fma_f32 v[26:27], v[152:153], v[54:55], v[26:27] op_sel:[0,1,0]
	v_pk_fma_f32 v[24:25], v[154:155], v[56:57], v[24:25] op_sel:[0,1,0]
	v_pk_fma_f32 v[22:23], v[152:153], v[56:57], v[22:23] op_sel:[0,1,0]
	v_pk_fma_f32 v[20:21], v[154:155], v[58:59], v[20:21] op_sel:[0,1,0]
	v_pk_fma_f32 v[18:19], v[152:153], v[58:59], v[18:19] op_sel:[0,1,0]
	v_pk_fma_f32 v[16:17], v[154:155], v[60:61], v[16:17] op_sel:[0,1,0]
	v_pk_fma_f32 v[14:15], v[152:153], v[60:61], v[14:15] op_sel:[0,1,0]
	v_pk_fma_f32 v[12:13], v[154:155], v[62:63], v[12:13] op_sel:[0,1,0]
	v_pk_fma_f32 v[10:11], v[152:153], v[62:63], v[10:11] op_sel:[0,1,0]
	v_pk_fma_f32 v[8:9], v[154:155], v[64:65], v[8:9] op_sel:[0,1,0]
	v_pk_fma_f32 v[6:7], v[152:153], v[64:65], v[6:7] op_sel:[0,1,0]
	v_pk_fma_f32 v[4:5], v[154:155], v[66:67], v[4:5] op_sel:[0,1,0]
	v_pk_fma_f32 v[2:3], v[152:153], v[66:67], v[2:3] op_sel:[0,1,0]
	v_add_u32_e32 v66, s9, v39
	ds_read2st64_b64 v[50:53], v66 offset1:8
	ds_read2st64_b64 v[54:57], v66 offset0:16 offset1:24
	ds_read2st64_b64 v[58:61], v66 offset0:32 offset1:40
	ds_read2st64_b64 v[62:65], v66 offset0:48 offset1:56
	ds_read_b64 v[66:67], v66 offset:32768
	s_add_i32 s9, s9, 8
	s_waitcnt vmcnt(10) lgkmcnt(0)
	v_pk_fma_f32 v[36:37], v[158:159], v[50:51], v[36:37] op_sel_hi:[1,0,1]
	v_pk_fma_f32 v[34:35], v[156:157], v[50:51], v[34:35] op_sel_hi:[1,0,1]
	v_pk_fma_f32 v[32:33], v[158:159], v[52:53], v[32:33] op_sel_hi:[1,0,1]
	v_pk_fma_f32 v[30:31], v[156:157], v[52:53], v[30:31] op_sel_hi:[1,0,1]
	v_pk_fma_f32 v[28:29], v[158:159], v[54:55], v[28:29] op_sel_hi:[1,0,1]
	v_pk_fma_f32 v[26:27], v[156:157], v[54:55], v[26:27] op_sel_hi:[1,0,1]
	v_pk_fma_f32 v[24:25], v[158:159], v[56:57], v[24:25] op_sel_hi:[1,0,1]
	v_pk_fma_f32 v[22:23], v[156:157], v[56:57], v[22:23] op_sel_hi:[1,0,1]
	v_pk_fma_f32 v[20:21], v[158:159], v[58:59], v[20:21] op_sel_hi:[1,0,1]
	v_pk_fma_f32 v[18:19], v[156:157], v[58:59], v[18:19] op_sel_hi:[1,0,1]
	v_pk_fma_f32 v[16:17], v[158:159], v[60:61], v[16:17] op_sel_hi:[1,0,1]
	v_pk_fma_f32 v[14:15], v[156:157], v[60:61], v[14:15] op_sel_hi:[1,0,1]
	v_pk_fma_f32 v[12:13], v[158:159], v[62:63], v[12:13] op_sel_hi:[1,0,1]
	v_pk_fma_f32 v[10:11], v[156:157], v[62:63], v[10:11] op_sel_hi:[1,0,1]
	v_pk_fma_f32 v[8:9], v[158:159], v[64:65], v[8:9] op_sel_hi:[1,0,1]
	v_pk_fma_f32 v[6:7], v[156:157], v[64:65], v[6:7] op_sel_hi:[1,0,1]
	v_pk_fma_f32 v[4:5], v[158:159], v[66:67], v[4:5] op_sel_hi:[1,0,1]
	v_pk_fma_f32 v[2:3], v[156:157], v[66:67], v[2:3] op_sel_hi:[1,0,1]
	v_pk_fma_f32 v[36:37], v[162:163], v[50:51], v[36:37] op_sel:[0,1,0]
	v_pk_fma_f32 v[34:35], v[160:161], v[50:51], v[34:35] op_sel:[0,1,0]
	v_pk_fma_f32 v[32:33], v[162:163], v[52:53], v[32:33] op_sel:[0,1,0]
	v_pk_fma_f32 v[30:31], v[160:161], v[52:53], v[30:31] op_sel:[0,1,0]
	v_pk_fma_f32 v[28:29], v[162:163], v[54:55], v[28:29] op_sel:[0,1,0]
	v_pk_fma_f32 v[26:27], v[160:161], v[54:55], v[26:27] op_sel:[0,1,0]
	v_pk_fma_f32 v[24:25], v[162:163], v[56:57], v[24:25] op_sel:[0,1,0]
	v_pk_fma_f32 v[22:23], v[160:161], v[56:57], v[22:23] op_sel:[0,1,0]
	v_pk_fma_f32 v[20:21], v[162:163], v[58:59], v[20:21] op_sel:[0,1,0]
	v_pk_fma_f32 v[18:19], v[160:161], v[58:59], v[18:19] op_sel:[0,1,0]
	v_pk_fma_f32 v[16:17], v[162:163], v[60:61], v[16:17] op_sel:[0,1,0]
	v_pk_fma_f32 v[14:15], v[160:161], v[60:61], v[14:15] op_sel:[0,1,0]
	v_pk_fma_f32 v[12:13], v[162:163], v[62:63], v[12:13] op_sel:[0,1,0]
	v_pk_fma_f32 v[10:11], v[160:161], v[62:63], v[10:11] op_sel:[0,1,0]
	v_pk_fma_f32 v[8:9], v[162:163], v[64:65], v[8:9] op_sel:[0,1,0]
	v_pk_fma_f32 v[6:7], v[160:161], v[64:65], v[6:7] op_sel:[0,1,0]
	v_pk_fma_f32 v[4:5], v[162:163], v[66:67], v[4:5] op_sel:[0,1,0]
	v_pk_fma_f32 v[2:3], v[160:161], v[66:67], v[2:3] op_sel:[0,1,0]
	v_add_u32_e32 v66, s9, v39
	ds_read2st64_b64 v[50:53], v66 offset1:8
	ds_read2st64_b64 v[54:57], v66 offset0:16 offset1:24
	ds_read2st64_b64 v[58:61], v66 offset0:32 offset1:40
	ds_read2st64_b64 v[62:65], v66 offset0:48 offset1:56
	ds_read_b64 v[66:67], v66 offset:32768
	s_add_i32 s9, s9, 8
	s_waitcnt vmcnt(8) lgkmcnt(0)
	v_pk_fma_f32 v[36:37], v[166:167], v[50:51], v[36:37] op_sel_hi:[1,0,1]
	v_pk_fma_f32 v[34:35], v[164:165], v[50:51], v[34:35] op_sel_hi:[1,0,1]
	v_pk_fma_f32 v[32:33], v[166:167], v[52:53], v[32:33] op_sel_hi:[1,0,1]
	v_pk_fma_f32 v[30:31], v[164:165], v[52:53], v[30:31] op_sel_hi:[1,0,1]
	v_pk_fma_f32 v[28:29], v[166:167], v[54:55], v[28:29] op_sel_hi:[1,0,1]
	v_pk_fma_f32 v[26:27], v[164:165], v[54:55], v[26:27] op_sel_hi:[1,0,1]
	v_pk_fma_f32 v[24:25], v[166:167], v[56:57], v[24:25] op_sel_hi:[1,0,1]
	v_pk_fma_f32 v[22:23], v[164:165], v[56:57], v[22:23] op_sel_hi:[1,0,1]
	v_pk_fma_f32 v[20:21], v[166:167], v[58:59], v[20:21] op_sel_hi:[1,0,1]
	v_pk_fma_f32 v[18:19], v[164:165], v[58:59], v[18:19] op_sel_hi:[1,0,1]
	v_pk_fma_f32 v[16:17], v[166:167], v[60:61], v[16:17] op_sel_hi:[1,0,1]
	v_pk_fma_f32 v[14:15], v[164:165], v[60:61], v[14:15] op_sel_hi:[1,0,1]
	v_pk_fma_f32 v[12:13], v[166:167], v[62:63], v[12:13] op_sel_hi:[1,0,1]
	v_pk_fma_f32 v[10:11], v[164:165], v[62:63], v[10:11] op_sel_hi:[1,0,1]
	v_pk_fma_f32 v[8:9], v[166:167], v[64:65], v[8:9] op_sel_hi:[1,0,1]
	v_pk_fma_f32 v[6:7], v[164:165], v[64:65], v[6:7] op_sel_hi:[1,0,1]
	v_pk_fma_f32 v[4:5], v[166:167], v[66:67], v[4:5] op_sel_hi:[1,0,1]
	v_pk_fma_f32 v[2:3], v[164:165], v[66:67], v[2:3] op_sel_hi:[1,0,1]
	v_pk_fma_f32 v[36:37], v[170:171], v[50:51], v[36:37] op_sel:[0,1,0]
	v_pk_fma_f32 v[34:35], v[168:169], v[50:51], v[34:35] op_sel:[0,1,0]
	v_pk_fma_f32 v[32:33], v[170:171], v[52:53], v[32:33] op_sel:[0,1,0]
	v_pk_fma_f32 v[30:31], v[168:169], v[52:53], v[30:31] op_sel:[0,1,0]
	v_pk_fma_f32 v[28:29], v[170:171], v[54:55], v[28:29] op_sel:[0,1,0]
	v_pk_fma_f32 v[26:27], v[168:169], v[54:55], v[26:27] op_sel:[0,1,0]
	v_pk_fma_f32 v[24:25], v[170:171], v[56:57], v[24:25] op_sel:[0,1,0]
	v_pk_fma_f32 v[22:23], v[168:169], v[56:57], v[22:23] op_sel:[0,1,0]
	v_pk_fma_f32 v[20:21], v[170:171], v[58:59], v[20:21] op_sel:[0,1,0]
	v_pk_fma_f32 v[18:19], v[168:169], v[58:59], v[18:19] op_sel:[0,1,0]
	v_pk_fma_f32 v[16:17], v[170:171], v[60:61], v[16:17] op_sel:[0,1,0]
	v_pk_fma_f32 v[14:15], v[168:169], v[60:61], v[14:15] op_sel:[0,1,0]
	v_pk_fma_f32 v[12:13], v[170:171], v[62:63], v[12:13] op_sel:[0,1,0]
	v_pk_fma_f32 v[10:11], v[168:169], v[62:63], v[10:11] op_sel:[0,1,0]
	v_pk_fma_f32 v[8:9], v[170:171], v[64:65], v[8:9] op_sel:[0,1,0]
	v_pk_fma_f32 v[6:7], v[168:169], v[64:65], v[6:7] op_sel:[0,1,0]
	v_pk_fma_f32 v[4:5], v[170:171], v[66:67], v[4:5] op_sel:[0,1,0]
	v_pk_fma_f32 v[2:3], v[168:169], v[66:67], v[2:3] op_sel:[0,1,0]
	v_add_u32_e32 v66, s9, v39
	ds_read2st64_b64 v[50:53], v66 offset1:8
	ds_read2st64_b64 v[54:57], v66 offset0:16 offset1:24
	ds_read2st64_b64 v[58:61], v66 offset0:32 offset1:40
	ds_read2st64_b64 v[62:65], v66 offset0:48 offset1:56
	ds_read_b64 v[66:67], v66 offset:32768
	s_add_i32 s9, s9, 8
	s_waitcnt vmcnt(6) lgkmcnt(0)
	v_pk_fma_f32 v[36:37], v[174:175], v[50:51], v[36:37] op_sel_hi:[1,0,1]
	v_pk_fma_f32 v[34:35], v[172:173], v[50:51], v[34:35] op_sel_hi:[1,0,1]
	v_pk_fma_f32 v[32:33], v[174:175], v[52:53], v[32:33] op_sel_hi:[1,0,1]
	v_pk_fma_f32 v[30:31], v[172:173], v[52:53], v[30:31] op_sel_hi:[1,0,1]
	v_pk_fma_f32 v[28:29], v[174:175], v[54:55], v[28:29] op_sel_hi:[1,0,1]
	v_pk_fma_f32 v[26:27], v[172:173], v[54:55], v[26:27] op_sel_hi:[1,0,1]
	v_pk_fma_f32 v[24:25], v[174:175], v[56:57], v[24:25] op_sel_hi:[1,0,1]
	v_pk_fma_f32 v[22:23], v[172:173], v[56:57], v[22:23] op_sel_hi:[1,0,1]
	v_pk_fma_f32 v[20:21], v[174:175], v[58:59], v[20:21] op_sel_hi:[1,0,1]
	v_pk_fma_f32 v[18:19], v[172:173], v[58:59], v[18:19] op_sel_hi:[1,0,1]
	v_pk_fma_f32 v[16:17], v[174:175], v[60:61], v[16:17] op_sel_hi:[1,0,1]
	v_pk_fma_f32 v[14:15], v[172:173], v[60:61], v[14:15] op_sel_hi:[1,0,1]
	v_pk_fma_f32 v[12:13], v[174:175], v[62:63], v[12:13] op_sel_hi:[1,0,1]
	v_pk_fma_f32 v[10:11], v[172:173], v[62:63], v[10:11] op_sel_hi:[1,0,1]
	v_pk_fma_f32 v[8:9], v[174:175], v[64:65], v[8:9] op_sel_hi:[1,0,1]
	v_pk_fma_f32 v[6:7], v[172:173], v[64:65], v[6:7] op_sel_hi:[1,0,1]
	v_pk_fma_f32 v[4:5], v[174:175], v[66:67], v[4:5] op_sel_hi:[1,0,1]
	v_pk_fma_f32 v[2:3], v[172:173], v[66:67], v[2:3] op_sel_hi:[1,0,1]
	v_pk_fma_f32 v[36:37], v[178:179], v[50:51], v[36:37] op_sel:[0,1,0]
	v_pk_fma_f32 v[34:35], v[176:177], v[50:51], v[34:35] op_sel:[0,1,0]
	v_pk_fma_f32 v[32:33], v[178:179], v[52:53], v[32:33] op_sel:[0,1,0]
	v_pk_fma_f32 v[30:31], v[176:177], v[52:53], v[30:31] op_sel:[0,1,0]
	v_pk_fma_f32 v[28:29], v[178:179], v[54:55], v[28:29] op_sel:[0,1,0]
	v_pk_fma_f32 v[26:27], v[176:177], v[54:55], v[26:27] op_sel:[0,1,0]
	v_pk_fma_f32 v[24:25], v[178:179], v[56:57], v[24:25] op_sel:[0,1,0]
	v_pk_fma_f32 v[22:23], v[176:177], v[56:57], v[22:23] op_sel:[0,1,0]
	v_pk_fma_f32 v[20:21], v[178:179], v[58:59], v[20:21] op_sel:[0,1,0]
	v_pk_fma_f32 v[18:19], v[176:177], v[58:59], v[18:19] op_sel:[0,1,0]
	v_pk_fma_f32 v[16:17], v[178:179], v[60:61], v[16:17] op_sel:[0,1,0]
	v_pk_fma_f32 v[14:15], v[176:177], v[60:61], v[14:15] op_sel:[0,1,0]
	v_pk_fma_f32 v[12:13], v[178:179], v[62:63], v[12:13] op_sel:[0,1,0]
	v_pk_fma_f32 v[10:11], v[176:177], v[62:63], v[10:11] op_sel:[0,1,0]
	v_pk_fma_f32 v[8:9], v[178:179], v[64:65], v[8:9] op_sel:[0,1,0]
	v_pk_fma_f32 v[6:7], v[176:177], v[64:65], v[6:7] op_sel:[0,1,0]
	v_pk_fma_f32 v[4:5], v[178:179], v[66:67], v[4:5] op_sel:[0,1,0]
	v_pk_fma_f32 v[2:3], v[176:177], v[66:67], v[2:3] op_sel:[0,1,0]
	v_add_u32_e32 v66, s9, v39
	ds_read2st64_b64 v[50:53], v66 offset1:8
	ds_read2st64_b64 v[54:57], v66 offset0:16 offset1:24
	ds_read2st64_b64 v[58:61], v66 offset0:32 offset1:40
	ds_read2st64_b64 v[62:65], v66 offset0:48 offset1:56
	ds_read_b64 v[66:67], v66 offset:32768
	s_add_i32 s9, s9, 8
	s_waitcnt vmcnt(4) lgkmcnt(0)
	v_pk_fma_f32 v[36:37], v[182:183], v[50:51], v[36:37] op_sel_hi:[1,0,1]
	v_pk_fma_f32 v[34:35], v[180:181], v[50:51], v[34:35] op_sel_hi:[1,0,1]
	v_pk_fma_f32 v[32:33], v[182:183], v[52:53], v[32:33] op_sel_hi:[1,0,1]
	v_pk_fma_f32 v[30:31], v[180:181], v[52:53], v[30:31] op_sel_hi:[1,0,1]
	v_pk_fma_f32 v[28:29], v[182:183], v[54:55], v[28:29] op_sel_hi:[1,0,1]
	v_pk_fma_f32 v[26:27], v[180:181], v[54:55], v[26:27] op_sel_hi:[1,0,1]
	v_pk_fma_f32 v[24:25], v[182:183], v[56:57], v[24:25] op_sel_hi:[1,0,1]
	v_pk_fma_f32 v[22:23], v[180:181], v[56:57], v[22:23] op_sel_hi:[1,0,1]
	v_pk_fma_f32 v[20:21], v[182:183], v[58:59], v[20:21] op_sel_hi:[1,0,1]
	v_pk_fma_f32 v[18:19], v[180:181], v[58:59], v[18:19] op_sel_hi:[1,0,1]
	v_pk_fma_f32 v[16:17], v[182:183], v[60:61], v[16:17] op_sel_hi:[1,0,1]
	v_pk_fma_f32 v[14:15], v[180:181], v[60:61], v[14:15] op_sel_hi:[1,0,1]
	v_pk_fma_f32 v[12:13], v[182:183], v[62:63], v[12:13] op_sel_hi:[1,0,1]
	v_pk_fma_f32 v[10:11], v[180:181], v[62:63], v[10:11] op_sel_hi:[1,0,1]
	v_pk_fma_f32 v[8:9], v[182:183], v[64:65], v[8:9] op_sel_hi:[1,0,1]
	v_pk_fma_f32 v[6:7], v[180:181], v[64:65], v[6:7] op_sel_hi:[1,0,1]
	v_pk_fma_f32 v[4:5], v[182:183], v[66:67], v[4:5] op_sel_hi:[1,0,1]
	v_pk_fma_f32 v[2:3], v[180:181], v[66:67], v[2:3] op_sel_hi:[1,0,1]
	v_pk_fma_f32 v[36:37], v[186:187], v[50:51], v[36:37] op_sel:[0,1,0]
	v_pk_fma_f32 v[34:35], v[184:185], v[50:51], v[34:35] op_sel:[0,1,0]
	v_pk_fma_f32 v[32:33], v[186:187], v[52:53], v[32:33] op_sel:[0,1,0]
	v_pk_fma_f32 v[30:31], v[184:185], v[52:53], v[30:31] op_sel:[0,1,0]
	v_pk_fma_f32 v[28:29], v[186:187], v[54:55], v[28:29] op_sel:[0,1,0]
	v_pk_fma_f32 v[26:27], v[184:185], v[54:55], v[26:27] op_sel:[0,1,0]
	v_pk_fma_f32 v[24:25], v[186:187], v[56:57], v[24:25] op_sel:[0,1,0]
	v_pk_fma_f32 v[22:23], v[184:185], v[56:57], v[22:23] op_sel:[0,1,0]
	v_pk_fma_f32 v[20:21], v[186:187], v[58:59], v[20:21] op_sel:[0,1,0]
	v_pk_fma_f32 v[18:19], v[184:185], v[58:59], v[18:19] op_sel:[0,1,0]
	v_pk_fma_f32 v[16:17], v[186:187], v[60:61], v[16:17] op_sel:[0,1,0]
	v_pk_fma_f32 v[14:15], v[184:185], v[60:61], v[14:15] op_sel:[0,1,0]
	v_pk_fma_f32 v[12:13], v[186:187], v[62:63], v[12:13] op_sel:[0,1,0]
	v_pk_fma_f32 v[10:11], v[184:185], v[62:63], v[10:11] op_sel:[0,1,0]
	v_pk_fma_f32 v[8:9], v[186:187], v[64:65], v[8:9] op_sel:[0,1,0]
	v_pk_fma_f32 v[6:7], v[184:185], v[64:65], v[6:7] op_sel:[0,1,0]
	v_pk_fma_f32 v[4:5], v[186:187], v[66:67], v[4:5] op_sel:[0,1,0]
	v_pk_fma_f32 v[2:3], v[184:185], v[66:67], v[2:3] op_sel:[0,1,0]
	v_add_u32_e32 v66, s9, v39
	ds_read2st64_b64 v[50:53], v66 offset1:8
	ds_read2st64_b64 v[54:57], v66 offset0:16 offset1:24
	ds_read2st64_b64 v[58:61], v66 offset0:32 offset1:40
	ds_read2st64_b64 v[62:65], v66 offset0:48 offset1:56
	ds_read_b64 v[66:67], v66 offset:32768
	s_add_i32 s9, s9, 8
	s_waitcnt vmcnt(2) lgkmcnt(0)
	v_pk_fma_f32 v[36:37], v[190:191], v[50:51], v[36:37] op_sel_hi:[1,0,1]
	v_pk_fma_f32 v[34:35], v[188:189], v[50:51], v[34:35] op_sel_hi:[1,0,1]
	v_pk_fma_f32 v[32:33], v[190:191], v[52:53], v[32:33] op_sel_hi:[1,0,1]
	v_pk_fma_f32 v[30:31], v[188:189], v[52:53], v[30:31] op_sel_hi:[1,0,1]
	v_pk_fma_f32 v[28:29], v[190:191], v[54:55], v[28:29] op_sel_hi:[1,0,1]
	v_pk_fma_f32 v[26:27], v[188:189], v[54:55], v[26:27] op_sel_hi:[1,0,1]
	v_pk_fma_f32 v[24:25], v[190:191], v[56:57], v[24:25] op_sel_hi:[1,0,1]
	v_pk_fma_f32 v[22:23], v[188:189], v[56:57], v[22:23] op_sel_hi:[1,0,1]
	v_pk_fma_f32 v[20:21], v[190:191], v[58:59], v[20:21] op_sel_hi:[1,0,1]
	v_pk_fma_f32 v[18:19], v[188:189], v[58:59], v[18:19] op_sel_hi:[1,0,1]
	v_pk_fma_f32 v[16:17], v[190:191], v[60:61], v[16:17] op_sel_hi:[1,0,1]
	v_pk_fma_f32 v[14:15], v[188:189], v[60:61], v[14:15] op_sel_hi:[1,0,1]
	v_pk_fma_f32 v[12:13], v[190:191], v[62:63], v[12:13] op_sel_hi:[1,0,1]
	v_pk_fma_f32 v[10:11], v[188:189], v[62:63], v[10:11] op_sel_hi:[1,0,1]
	v_pk_fma_f32 v[8:9], v[190:191], v[64:65], v[8:9] op_sel_hi:[1,0,1]
	v_pk_fma_f32 v[6:7], v[188:189], v[64:65], v[6:7] op_sel_hi:[1,0,1]
	v_pk_fma_f32 v[4:5], v[190:191], v[66:67], v[4:5] op_sel_hi:[1,0,1]
	v_pk_fma_f32 v[2:3], v[188:189], v[66:67], v[2:3] op_sel_hi:[1,0,1]
	v_pk_fma_f32 v[36:37], v[194:195], v[50:51], v[36:37] op_sel:[0,1,0]
	v_pk_fma_f32 v[34:35], v[192:193], v[50:51], v[34:35] op_sel:[0,1,0]
	v_pk_fma_f32 v[32:33], v[194:195], v[52:53], v[32:33] op_sel:[0,1,0]
	v_pk_fma_f32 v[30:31], v[192:193], v[52:53], v[30:31] op_sel:[0,1,0]
	v_pk_fma_f32 v[28:29], v[194:195], v[54:55], v[28:29] op_sel:[0,1,0]
	v_pk_fma_f32 v[26:27], v[192:193], v[54:55], v[26:27] op_sel:[0,1,0]
	v_pk_fma_f32 v[24:25], v[194:195], v[56:57], v[24:25] op_sel:[0,1,0]
	v_pk_fma_f32 v[22:23], v[192:193], v[56:57], v[22:23] op_sel:[0,1,0]
	v_pk_fma_f32 v[20:21], v[194:195], v[58:59], v[20:21] op_sel:[0,1,0]
	v_pk_fma_f32 v[18:19], v[192:193], v[58:59], v[18:19] op_sel:[0,1,0]
	v_pk_fma_f32 v[16:17], v[194:195], v[60:61], v[16:17] op_sel:[0,1,0]
	v_pk_fma_f32 v[14:15], v[192:193], v[60:61], v[14:15] op_sel:[0,1,0]
	v_pk_fma_f32 v[12:13], v[194:195], v[62:63], v[12:13] op_sel:[0,1,0]
	v_pk_fma_f32 v[10:11], v[192:193], v[62:63], v[10:11] op_sel:[0,1,0]
	v_pk_fma_f32 v[8:9], v[194:195], v[64:65], v[8:9] op_sel:[0,1,0]
	v_pk_fma_f32 v[6:7], v[192:193], v[64:65], v[6:7] op_sel:[0,1,0]
	v_pk_fma_f32 v[4:5], v[194:195], v[66:67], v[4:5] op_sel:[0,1,0]
	v_pk_fma_f32 v[2:3], v[192:193], v[66:67], v[2:3] op_sel:[0,1,0]
	v_add_u32_e32 v66, s9, v39
	ds_read2st64_b64 v[50:53], v66 offset1:8
	ds_read2st64_b64 v[54:57], v66 offset0:16 offset1:24
	ds_read2st64_b64 v[58:61], v66 offset0:32 offset1:40
	ds_read2st64_b64 v[62:65], v66 offset0:48 offset1:56
	ds_read_b64 v[66:67], v66 offset:32768
	s_add_i32 s9, s9, 8
	s_waitcnt vmcnt(0) lgkmcnt(0)
	v_pk_fma_f32 v[36:37], v[198:199], v[50:51], v[36:37] op_sel_hi:[1,0,1]
	v_pk_fma_f32 v[34:35], v[196:197], v[50:51], v[34:35] op_sel_hi:[1,0,1]
	v_pk_fma_f32 v[32:33], v[198:199], v[52:53], v[32:33] op_sel_hi:[1,0,1]
	v_pk_fma_f32 v[30:31], v[196:197], v[52:53], v[30:31] op_sel_hi:[1,0,1]
	v_pk_fma_f32 v[28:29], v[198:199], v[54:55], v[28:29] op_sel_hi:[1,0,1]
	v_pk_fma_f32 v[26:27], v[196:197], v[54:55], v[26:27] op_sel_hi:[1,0,1]
	v_pk_fma_f32 v[24:25], v[198:199], v[56:57], v[24:25] op_sel_hi:[1,0,1]
	v_pk_fma_f32 v[22:23], v[196:197], v[56:57], v[22:23] op_sel_hi:[1,0,1]
	v_pk_fma_f32 v[20:21], v[198:199], v[58:59], v[20:21] op_sel_hi:[1,0,1]
	v_pk_fma_f32 v[18:19], v[196:197], v[58:59], v[18:19] op_sel_hi:[1,0,1]
	v_pk_fma_f32 v[16:17], v[198:199], v[60:61], v[16:17] op_sel_hi:[1,0,1]
	v_pk_fma_f32 v[14:15], v[196:197], v[60:61], v[14:15] op_sel_hi:[1,0,1]
	v_pk_fma_f32 v[12:13], v[198:199], v[62:63], v[12:13] op_sel_hi:[1,0,1]
	v_pk_fma_f32 v[10:11], v[196:197], v[62:63], v[10:11] op_sel_hi:[1,0,1]
	v_pk_fma_f32 v[8:9], v[198:199], v[64:65], v[8:9] op_sel_hi:[1,0,1]
	v_pk_fma_f32 v[6:7], v[196:197], v[64:65], v[6:7] op_sel_hi:[1,0,1]
	v_pk_fma_f32 v[4:5], v[198:199], v[66:67], v[4:5] op_sel_hi:[1,0,1]
	v_pk_fma_f32 v[2:3], v[196:197], v[66:67], v[2:3] op_sel_hi:[1,0,1]
	v_pk_fma_f32 v[36:37], v[202:203], v[50:51], v[36:37] op_sel:[0,1,0]
	v_pk_fma_f32 v[34:35], v[200:201], v[50:51], v[34:35] op_sel:[0,1,0]
	v_pk_fma_f32 v[32:33], v[202:203], v[52:53], v[32:33] op_sel:[0,1,0]
	v_pk_fma_f32 v[30:31], v[200:201], v[52:53], v[30:31] op_sel:[0,1,0]
	v_pk_fma_f32 v[28:29], v[202:203], v[54:55], v[28:29] op_sel:[0,1,0]
	v_pk_fma_f32 v[26:27], v[200:201], v[54:55], v[26:27] op_sel:[0,1,0]
	v_pk_fma_f32 v[24:25], v[202:203], v[56:57], v[24:25] op_sel:[0,1,0]
	v_pk_fma_f32 v[22:23], v[200:201], v[56:57], v[22:23] op_sel:[0,1,0]
	v_pk_fma_f32 v[20:21], v[202:203], v[58:59], v[20:21] op_sel:[0,1,0]
	v_pk_fma_f32 v[18:19], v[200:201], v[58:59], v[18:19] op_sel:[0,1,0]
	v_pk_fma_f32 v[16:17], v[202:203], v[60:61], v[16:17] op_sel:[0,1,0]
	v_pk_fma_f32 v[14:15], v[200:201], v[60:61], v[14:15] op_sel:[0,1,0]
	v_pk_fma_f32 v[12:13], v[202:203], v[62:63], v[12:13] op_sel:[0,1,0]
	v_pk_fma_f32 v[10:11], v[200:201], v[62:63], v[10:11] op_sel:[0,1,0]
	v_pk_fma_f32 v[8:9], v[202:203], v[64:65], v[8:9] op_sel:[0,1,0]
	v_pk_fma_f32 v[6:7], v[200:201], v[64:65], v[6:7] op_sel:[0,1,0]
	v_pk_fma_f32 v[4:5], v[202:203], v[66:67], v[4:5] op_sel:[0,1,0]
	v_pk_fma_f32 v[2:3], v[200:201], v[66:67], v[2:3] op_sel:[0,1,0]
	v_lshlrev_b32_e32 v39, 4, v38
	s_movk_i32 s9, 0x1200
	v_and_b32_e32 v39, 0x1f0, v39
	v_mul_lo_u32 v0, v0, s9
	s_movk_i32 s9, 0x480
	v_add3_u32 v0, 16, v39, v0
	v_cmp_gt_i32_e32 vcc, s9, v38
	ds_write_b128 v0, v[34:37] offset:36864
	ds_write_b128 v0, v[30:33] offset:37376
	ds_write_b128 v0, v[26:29] offset:37888
	ds_write_b128 v0, v[22:25] offset:38400
	ds_write_b128 v0, v[18:21] offset:38912
	ds_write_b128 v0, v[14:17] offset:39424
	ds_write_b128 v0, v[10:13] offset:39936
	ds_write_b128 v0, v[6:9] offset:40448
	ds_write_b128 v0, v[2:5] offset:40960
	s_waitcnt lgkmcnt(0)
	s_barrier
	s_and_saveexec_b64 s[14:15], vcc
	s_cbranch_execz .LBB0_932
	s_add_u32 s12, s6, s12
	s_mul_i32 s9, s8, 0x2400
	s_addc_u32 s13, s7, s13
	s_add_i32 s9, s9, s10
	v_readlane_b32 s10, v255, 7
	v_readlane_b32 s11, v255, 8
	s_load_dwordx2 s[10:11], s[10:11], 0x28
	v_and_b32_e32 v0, 0x7f, v38
	v_or_b32_e32 v2, s9, v0
	v_ashrrev_i32_e32 v3, 31, v2
	v_lshlrev_b32_e32 v0, 2, v0
	s_mul_i32 s8, s8, 9
	s_waitcnt lgkmcnt(0)
	v_lshl_add_u64 v[2:3], v[2:3], 2, s[10:11]
	v_add_u32_e32 v6, 16, v0
	v_lshl_add_u64 v[4:5], s[12:13], 0, v[0:1]
	s_mov_b64 s[10:11], 0
